# position FFT: last pass stores pairs permuted inside their 256-byte block so the digit-reversed read-out no longer hits one LDS bank pair
# speedup vs baseline: 1.0067x; 1.0067x over previous
; __device__ __forceinline__ void phase_fft(const Params& p, LAS unsigned char* lds) {
;     ...
;         for (int j = tid; j < 4096; j += 512) {
;             { const f32x2 a = X0[2 * j], bb = X0[2 * j + 1]; X0[2 * j] = a + bb; X0[2 * j + 1] = a - bb; }
;             { const f32x2 a = X1[2 * j], bb = X1[2 * j + 1]; X1[2 * j] = a + bb; X1[2 * j + 1] = a - bb; }
;         }
;         __syncthreads();
;         const float sc = 0.5f * 0.011048543456039806f;
;         for (int k = tid; k < SEQ; k += 512) {
;             const unsigned kb = (unsigned)((SEQ - k) & (SEQ - 1));
;             const unsigned ya_ = __brev((unsigned)k & 0xFFFu) >> 20, yb_ = __brev(kb & 0xFFFu) >> 20;
;             const int ra = (int)(((((ya_ & 0xAAAu) >> 1) | ((ya_ & 0x555u) << 1)) << 1) | ((unsigned)k >> 12));
;             const int rb = (int)(((((yb_ & 0xAAAu) >> 1) | ((yb_ & 0x555u) << 1)) << 1) | (kb >> 12));
;             const f32x2 za = X0[ra], zb = X0[rb], ya = X1[ra], yb = X1[rb];
;             h16x4 orr, oi;
;             orr[0] = (h16)((za[0] + zb[0]) * sc); oi[0] = (h16)((za[1] - zb[1]) * sc);
;             orr[1] = (h16)((za[1] + zb[1]) * sc); oi[1] = (h16)((zb[0] - za[0]) * sc);
;             orr[2] = (h16)((ya[0] + yb[0]) * sc); oi[2] = (h16)((ya[1] - yb[1]) * sc);
;             orr[3] = (h16)((ya[1] + yb[1]) * sc); oi[3] = (h16)((yb[0] - ya[0]) * sc);
;             *(h16x4*)(SPr + ((size_t)(it & 127) * NTOK + b * SEQ + k) * 4) = orr; *(h16x4*)(SPi + ((size_t)(it & 127) * NTOK + b * SEQ + k) * 4) = oi;
;         }
.LBB0_587:
	ds_read_b128 v[10:13], v2
	v_add_u32_e32 v9, 0x10000, v2
	ds_read_b128 v[14:17], v9
	v_lshrrev_b32_e32 v100, 8, v2
	v_and_b32_e32 v100, 0xf0, v100
	v_xor_b32_e32 v101, v2, v100
	v_add_u32_e32 v102, 0x10000, v101
	v_add_u32_e32 v3, 0x200, v3
	v_cmp_lt_u32_e32 vcc, s22, v3
	s_waitcnt lgkmcnt(1)
	v_pk_add_f32 v[18:19], v[10:11], v[12:13]
	v_pk_add_f32 v[20:21], v[10:11], v[12:13] neg_lo:[0,1] neg_hi:[0,1]
	ds_write_b128 v101, v[18:21]
	s_waitcnt lgkmcnt(1)
	v_pk_add_f32 v[10:11], v[14:15], v[16:17]
	v_pk_add_f32 v[12:13], v[14:15], v[16:17] neg_lo:[0,1] neg_hi:[0,1]
	s_or_b64 s[0:1], vcc, s[0:1]
	v_add_u32_e32 v2, 0x2000, v2
	ds_write_b128 v102, v[10:13]
	s_andn2_b64 exec, exec, s[0:1]
	s_cbranch_execnz .LBB0_587
	s_or_b64 exec, exec, s[0:1]
	v_lshl_add_u64 v[0:1], s[70:71], 0, v[0:1]
	s_mov_b64 s[12:13], 0
	v_mov_b32_e32 v2, v8
	v_mov_b32_e32 v3, v130
	s_waitcnt lgkmcnt(0)
	s_barrier
.LBB0_589:
	v_and_b32_e32 v9, 0xfff, v3
	v_and_b32_e32 v11, 0xfff, v2
	v_add_u32_e32 v14, 0x200, v3
	v_bfrev_b32_e32 v9, v9
	v_lshrrev_b32_e32 v12, 12, v3
	v_cmp_lt_u32_e64 s[0:1], s19, v3
	v_bfrev_b32_e32 v15, v11
	v_mov_b32_e32 v3, v14
	v_lshrrev_b32_e32 v14, 21, v9
	v_lshrrev_b32_e32 v9, 19, v9
	v_lshrrev_b32_e32 v16, 21, v15
	v_lshrrev_b32_e32 v15, 19, v15
	v_and_b32_e32 v9, 0xaaa, v9
	v_lshrrev_b32_e32 v13, 9, v2
	v_and_b32_e32 v15, 0xaaa, v15
	v_and_or_b32 v9, v14, s23, v9
	v_and_b32_e32 v13, 8, v13
	v_and_or_b32 v14, v16, s23, v15
	v_lshlrev_b32_e32 v9, 1, v9
	v_lshl_or_b32 v13, v14, 4, v13
	v_add_lshl_u32 v9, v9, v12, 3
	v_lshrrev_b32_e32 v100, 8, v9
	v_lshrrev_b32_e32 v101, 8, v13
	v_and_b32_e32 v100, 0xf0, v100
	v_and_b32_e32 v101, 0xf0, v101
	v_xor_b32_e32 v9, v9, v100
	v_xor_b32_e32 v13, v13, v101
	v_add_u32_e32 v14, 0, v13
	v_add_u32_e32 v18, s20, v13
	v_add_u32_e32 v12, 0, v9
	v_add_u32_e32 v9, s20, v9
	ds_read_b64 v[12:13], v12
	ds_read_b64 v[14:15], v14
	ds_read_b64 v[16:17], v9
	ds_read_b64 v[18:19], v18
	v_add_co_u32_e32 v10, vcc, 0xe800000, v0
	s_waitcnt lgkmcnt(2)
	v_pk_add_f32 v[20:21], v[12:13], v[14:15]
	v_pk_mov_b32 v[22:23], v[12:13], v[14:15] op_sel:[1,0]
	v_pk_mov_b32 v[12:13], v[14:15], v[12:13] op_sel:[1,0]
	s_waitcnt lgkmcnt(0)
	v_pk_add_f32 v[14:15], v[16:17], v[18:19]
	v_pk_mov_b32 v[24:25], v[16:17], v[18:19] op_sel:[1,0]
	v_pk_mov_b32 v[16:17], v[18:19], v[16:17] op_sel:[1,0]
	v_pk_mul_f32 v[18:19], v[20:21], s[10:11] op_sel_hi:[1,0]
	v_pk_add_f32 v[12:13], v[22:23], v[12:13] neg_lo:[0,1] neg_hi:[0,1]
	v_pk_mul_f32 v[14:15], v[14:15], s[10:11] op_sel_hi:[1,0]
	v_pk_add_f32 v[16:17], v[24:25], v[16:17] neg_lo:[0,1] neg_hi:[0,1]
	v_cvt_pk_f16_f32 v18, v18, v19
	v_pk_mul_f32 v[12:13], v[12:13], s[10:11] op_sel_hi:[1,0]
	v_cvt_pk_f16_f32 v19, v14, v15
	v_pk_mul_f32 v[14:15], v[16:17], s[10:11] op_sel_hi:[1,0]
	v_add_u32_e32 v2, 0xfffffe00, v2
	v_addc_co_u32_e32 v11, vcc, 0, v1, vcc
	s_or_b64 s[12:13], s[0:1], s[12:13]
	v_cvt_pk_f16_f32 v12, v12, v13
	v_cvt_pk_f16_f32 v13, v14, v15
	global_store_dwordx2 v[0:1], v[18:19], off
	v_lshl_add_u64 v[0:1], v[0:1], 0, s[8:9]
	global_store_dwordx2 v[10:11], v[12:13], off
	s_andn2_b64 exec, exec, s[12:13]
	s_cbranch_execnz .LBB0_589
	s_or_b64 exec, exec, s[12:13]
	s_add_i32 s24, s24, s74
	s_add_i32 s11, s11, s14
	s_add_i32 s15, s15, s18
	s_cmpk_gt_i32 s24, 0xff
	s_cbranch_scc0 .LBB0_578
